# dilated qkv epilogue: rope tables via LDS-DMA prefetch into idle LDS, rope-wave stores deferred, one epilogue barrier so table fetches enter the memory queue before tile stores
# speedup vs baseline: 1.0036x; 1.0036x over previous
; #define PG8_G __attribute__((address_space(1)))
; __device__ __forceinline__ u32x4 pack8bf(const f32x4 a, const f32x4 b) { u32x4 w; w.x = cvt_pk_bf16(a[0], a[1]); w.y = cvt_pk_bf16(a[2], a[3]); w.z = cvt_pk_bf16(b[0], b[1]); w.w = cvt_pk_bf16(b[2], b[3]); return w; }
;     __device__ __forceinline__ void operator()(const f32x4 (&acc)[2][2][4][2], const Unit& u, int wr, int wc, int fr, int fq, int ui) const {
;         const int row0 = u.pm * BM + wr * 64 + fr;
;         const int g = u.pn / 24, rem = u.pn - g * 24, t = rem >> 3, T = rem & 7, sh = 2 * g;
;         float r[2][4]; load_rs(r, rsl, wr, fr);
;         const size_t plane = ((size_t)(g * 3 + t) * 16 + 2 * T) * 4;
;         if (t == 2 || wc != 0) {
;             const int dim0 = wc * 32 + 8 * fq;
; #pragma unroll
;             for (int ai = 0; ai < 2; ++ai)
; #pragma unroll
;                 for (int m = 0; m < 4; ++m) { const int row = row0 + ai * HALF + m * 16, b = row >> 12, s = row & 4095, sp = ((s & ((1 << sh) - 1)) << (12 - sh)) + (s >> sh);
; #pragma unroll
;                     for (int bj = 0; bj < 2; ++bj) *(PG8_G u32x4*)(O + ((plane + bj * 4 + b) * 4096 + sp) * 128 + dim0) = pack8bf(acc[ai][bj][m][0] * r[ai][m], acc[ai][bj][m][1] * r[ai][m]); }
;         } else {
;             const int hh = fq >> 1, i0 = 8 * (fq & 1);
; #pragma unroll
;             for (int ai = 0; ai < 2; ++ai)
; #pragma unroll
;                 for (int m = 0; m < 4; ++m) { const int row = row0 + ai * HALF + m * 16, b = row >> 12, s = row & 4095, sp = ((s & ((1 << sh) - 1)) << (12 - sh)) + (s >> sh);
;                     const f32x4 c0 = *(const PG8_G f32x4*)(cosT + (size_t)row * 16 + i0), c1 = *(const PG8_G f32x4*)(cosT + (size_t)row * 16 + i0 + 4);
;                     const f32x4 s0 = *(const PG8_G f32x4*)(sinT + (size_t)row * 16 + i0), s1 = *(const PG8_G f32x4*)(sinT + (size_t)row * 16 + i0 + 4);
;                     const f32x4 x1a = acc[ai][0][m][0] * r[ai][m], x1b = acc[ai][0][m][1] * r[ai][m], x2a = acc[ai][1][m][0] * r[ai][m], x2b = acc[ai][1][m][1] * r[ai][m];
;                     const f32x4 y1a = x1a * c0 - x2a * s0, y1b = x1b * c1 - x2b * s1, y2a = x2a * c0 + x1a * s0, y2b = x2b * c1 + x1b * s1;
;                     bf16_t* dst = O + ((plane + hh * 4 + b) * 4096 + sp) * 128 + i0;
;                     *(PG8_G u32x4*)dst = pack8bf(y1a, y1b); *(PG8_G u32x4*)(dst + 16) = pack8bf(y2a, y2b); }
.LBB0_759:
	v_ashrrev_i32_e32 v167, 31, v166
	v_lshlrev_b64 v[132:133], 6, v[166:167]
	v_lshl_add_u64 v[134:135], v[148:149], 0, v[132:133]
	global_load_dwordx4 v[178:181], v[134:135], off
	global_load_dwordx4 v[182:185], v[134:135], off offset:16
	v_lshl_add_u64 v[132:133], v[146:147], 0, v[132:133]
	global_load_dwordx4 v[186:189], v[132:133], off
	global_load_dwordx4 v[190:193], v[132:133], off offset:16
	s_mov_b64 s[98:99], 0x2000
	v_lshl_add_u64 v[236:237], v[134:135], 0, s[98:99]
	v_lshl_add_u64 v[238:239], v[132:133], 0, s[98:99]
	v_readfirstlane_b32 s100, v0
	s_nop 3
	s_lshr_b32 s100, s100, 8
	s_cmp_eq_u32 s100, 0
	s_mov_b32 s101, 0x20400
	s_cselect_b32 s100, 0x24000, s101
	v_and_b32_e32 v240, 31, v0
	v_lshl_add_u32 v240, v240, 4, s100
	s_mov_b64 s[98:99], exec
	s_mov_b32 exec_hi, 0
	s_mov_b32 exec_lo, -1
	s_sub_i32 m0, s100, 1024
	s_nop 0
	global_load_lds_dwordx4 v[134:135], off offset:1024
	s_sub_i32 m0, s100, 528
	s_nop 0
	global_load_lds_dwordx4 v[134:135], off offset:1040
	s_add_i32 m0, s100, 0
	s_nop 0
	global_load_lds_dwordx4 v[132:133], off offset:1024
	s_add_i32 m0, s100, 496
	s_nop 0
	global_load_lds_dwordx4 v[132:133], off offset:1040
	s_add_i32 m0, s100, 0
	s_nop 0
	global_load_lds_dwordx4 v[134:135], off offset:2048
	s_add_i32 m0, s100, 496
	s_nop 0
	global_load_lds_dwordx4 v[134:135], off offset:2064
	s_add_i32 m0, s100, 1024
	s_nop 0
	global_load_lds_dwordx4 v[132:133], off offset:2048
	s_add_i32 m0, s100, 1520
	s_nop 0
	global_load_lds_dwordx4 v[132:133], off offset:2064
	s_add_i32 m0, s100, 1024
	s_nop 0
	global_load_lds_dwordx4 v[134:135], off offset:3072
	s_add_i32 m0, s100, 1520
	s_nop 0
	global_load_lds_dwordx4 v[134:135], off offset:3088
	s_add_i32 m0, s100, 2048
	s_nop 0
	global_load_lds_dwordx4 v[132:133], off offset:3072
	s_add_i32 m0, s100, 2544
	s_nop 0
	global_load_lds_dwordx4 v[132:133], off offset:3088
	s_add_i32 m0, s100, 6144
	s_nop 0
	global_load_lds_dwordx4 v[236:237], off
	s_add_i32 m0, s100, 6640
	s_nop 0
	global_load_lds_dwordx4 v[236:237], off offset:16
	s_add_i32 m0, s100, 7168
	s_nop 0
	global_load_lds_dwordx4 v[238:239], off
	s_add_i32 m0, s100, 7664
	s_nop 0
	global_load_lds_dwordx4 v[238:239], off offset:16
	s_add_i32 m0, s100, 7168
	s_nop 0
	global_load_lds_dwordx4 v[236:237], off offset:1024
	s_add_i32 m0, s100, 7664
	s_nop 0
	global_load_lds_dwordx4 v[236:237], off offset:1040
	s_add_i32 m0, s100, 8192
	s_nop 0
	global_load_lds_dwordx4 v[238:239], off offset:1024
	s_add_i32 m0, s100, 8688
	s_nop 0
	global_load_lds_dwordx4 v[238:239], off offset:1040
	s_add_i32 m0, s100, 8192
	s_nop 0
	global_load_lds_dwordx4 v[236:237], off offset:2048
	s_add_i32 m0, s100, 8688
	s_nop 0
	global_load_lds_dwordx4 v[236:237], off offset:2064
	s_add_i32 m0, s100, 9216
	s_nop 0
	global_load_lds_dwordx4 v[238:239], off offset:2048
	s_add_i32 m0, s100, 9712
	s_nop 0
	global_load_lds_dwordx4 v[238:239], off offset:2064
	s_add_i32 m0, s100, 9216
	s_nop 0
	global_load_lds_dwordx4 v[236:237], off offset:3072
	s_add_i32 m0, s100, 9712
	s_nop 0
	global_load_lds_dwordx4 v[236:237], off offset:3088
	s_add_i32 m0, s100, 10240
	s_nop 0
	global_load_lds_dwordx4 v[238:239], off offset:3072
	s_add_i32 m0, s100, 10736
	s_nop 0
	global_load_lds_dwordx4 v[238:239], off offset:3088
	s_mov_b64 exec, s[98:99]
	s_barrier
	s_sub_i32 s52, 12, s44
	s_ashr_i32 s54, s25, 12
	v_mov_b32_e32 v133, s69
	v_or_b32_e32 v132, s68, v144
	v_lshlrev_b32_e32 v134, s52, v166
	s_ashr_i32 s55, s54, 31
	v_and_b32_e32 v167, 0xfff, v134
	v_lshl_add_u64 v[134:135], v[132:133], 0, s[54:55]
	v_lshlrev_b64 v[134:135], 20, v[134:135]
	v_or_b32_e32 v172, 16, v166
	s_waitcnt lgkmcnt(0)
	v_pk_mul_f32 v[194:195], v[130:131], v[164:165] op_sel_hi:[1,0]
	v_pk_mul_f32 v[196:197], v[128:129], v[164:165] op_sel_hi:[1,0]
	v_pk_mul_f32 v[208:209], v[122:123], v[164:165] op_sel_hi:[1,0]
	v_pk_mul_f32 v[210:211], v[120:121], v[164:165] op_sel_hi:[1,0]
	v_pk_mul_f32 v[212:213], v[114:115], v[164:165] op_sel_hi:[1,0]
	v_pk_mul_f32 v[214:215], v[112:113], v[164:165] op_sel_hi:[1,0]
	v_add_lshl_u32 v200, v167, v157, 8
	v_lshl_add_u64 v[134:135], s[50:51], 0, v[134:135]
	v_pk_mul_f32 v[198:199], v[126:127], v[164:165] op_sel_hi:[1,0]
	v_pk_mul_f32 v[206:207], v[124:125], v[164:165] op_sel_hi:[1,0]
	v_mov_b32_e32 v155, v201
	v_ashrrev_i32_e32 v173, 31, v172
	v_lshl_add_u64 v[220:221], v[134:135], 0, v[200:201]
	v_lshlrev_b64 v[216:217], 6, v[172:173]
	v_lshl_add_u64 v[220:221], v[220:221], 0, v[154:155]
	v_lshl_add_u64 v[218:219], v[148:149], 0, v[216:217]
	s_movk_i32 s48, 0xfdf
	v_bitop3_b32 v167, v166, s48, 16 bitop3:0xc8
	v_lshlrev_b32_e32 v169, s52, v172
	v_lshrrev_b32_e32 v167, s44, v167
	v_and_b32_e32 v169, 0xfff, v169
	v_add_lshl_u32 v200, v169, v167, 8
	s_movk_i32 s48, 0xfef
	v_bitop3_b32 v167, v166, s48, 32 bitop3:0xc8
	v_lshrrev_b32_e32 v167, s44, v167
	v_ashrrev_i32_e32 v171, 31, v170
	s_waitcnt vmcnt(28)
; #define PG8_G __attribute__((address_space(1)))
; __device__ __forceinline__ u32x4 pack8bf(const f32x4 a, const f32x4 b) { u32x4 w; w.x = cvt_pk_bf16(a[0], a[1]); w.y = cvt_pk_bf16(a[2], a[3]); w.z = cvt_pk_bf16(b[0], b[1]); w.w = cvt_pk_bf16(b[2], b[3]); return w; }
;     __device__ __forceinline__ void operator()(const f32x4 (&acc)[2][2][4][2], const Unit& u, int wr, int wc, int fr, int fq, int ui) const {
;     ...
;             const int hh = fq >> 1, i0 = 8 * (fq & 1);
; #pragma unroll
;             for (int ai = 0; ai < 2; ++ai)
; #pragma unroll
;                 for (int m = 0; m < 4; ++m) { const int row = row0 + ai * HALF + m * 16, b = row >> 12, s = row & 4095, sp = ((s & ((1 << sh) - 1)) << (12 - sh)) + (s >> sh);
;                     const f32x4 c0 = *(const PG8_G f32x4*)(cosT + (size_t)row * 16 + i0), c1 = *(const PG8_G f32x4*)(cosT + (size_t)row * 16 + i0 + 4);
;                     const f32x4 s0 = *(const PG8_G f32x4*)(sinT + (size_t)row * 16 + i0), s1 = *(const PG8_G f32x4*)(sinT + (size_t)row * 16 + i0 + 4);
;                     const f32x4 x1a = acc[ai][0][m][0] * r[ai][m], x1b = acc[ai][0][m][1] * r[ai][m], x2a = acc[ai][1][m][0] * r[ai][m], x2b = acc[ai][1][m][1] * r[ai][m];
;                     const f32x4 y1a = x1a * c0 - x2a * s0, y1b = x1b * c1 - x2b * s1, y2a = x2a * c0 + x1a * s0, y2b = x2b * c1 + x1b * s1;
;                     bf16_t* dst = O + ((plane + hh * 4 + b) * 4096 + sp) * 128 + i0;
;                     *(PG8_G u32x4*)dst = pack8bf(y1a, y1b); *(PG8_G u32x4*)(dst + 16) = pack8bf(y2a, y2b); }
	v_pk_mul_f32 v[222:223], v[208:209], v[180:181]
	v_pk_mul_f32 v[224:225], v[210:211], v[178:179]
	v_pk_mul_f32 v[232:233], v[212:213], v[184:185]
	v_pk_mul_f32 v[234:235], v[214:215], v[182:183]
	v_pk_mul_f32 v[180:181], v[194:195], v[180:181]
	v_pk_mul_f32 v[178:179], v[196:197], v[178:179]
	v_pk_mul_f32 v[184:185], v[198:199], v[184:185]
	v_pk_mul_f32 v[182:183], v[206:207], v[182:183]
	v_pk_fma_f32 v[194:195], v[194:195], v[188:189], v[222:223] neg_lo:[0,0,1] neg_hi:[0,0,1]
	v_pk_fma_f32 v[196:197], v[196:197], v[186:187], v[224:225] neg_lo:[0,0,1] neg_hi:[0,0,1]
	v_pk_fma_f32 v[198:199], v[198:199], v[192:193], v[232:233] neg_lo:[0,0,1] neg_hi:[0,0,1]
	v_pk_fma_f32 v[206:207], v[206:207], v[190:191], v[234:235] neg_lo:[0,0,1] neg_hi:[0,0,1]
	v_pk_fma_f32 v[188:189], v[208:209], v[188:189], v[180:181]
	v_pk_fma_f32 v[186:187], v[210:211], v[186:187], v[178:179]
	v_cvt_pk_bf16_f32 v178, v196, v197
	v_cvt_pk_bf16_f32 v179, v194, v195
	v_cvt_pk_bf16_f32 v180, v206, v207
	v_cvt_pk_bf16_f32 v181, v198, v199
	v_pk_fma_f32 v[184:185], v[212:213], v[192:193], v[184:185]
	v_pk_fma_f32 v[182:183], v[214:215], v[190:191], v[182:183]
	v_mov_b32_e32 v112, v178
	v_mov_b32_e32 v113, v179
	v_mov_b32_e32 v114, v180
	v_mov_b32_e32 v115, v181
	v_mov_b32_e32 v124, v220
	v_mov_b32_e32 v125, v221
	v_lshl_add_u64 v[190:191], v[146:147], 0, v[216:217]
	v_mov_b32_e32 v196, v165
	v_cvt_pk_bf16_f32 v178, v186, v187
	v_cvt_pk_bf16_f32 v179, v188, v189
	v_cvt_pk_bf16_f32 v180, v182, v183
	v_cvt_pk_bf16_f32 v181, v184, v185
	v_mov_b32_e32 v120, v178
	v_mov_b32_e32 v121, v179
	v_mov_b32_e32 v122, v180
	v_mov_b32_e32 v123, v181
	s_waitcnt vmcnt(24)
	ds_read_b128 v[178:181], v240
	ds_read_b128 v[182:185], v240 offset:512
	ds_read_b128 v[186:189], v240 offset:1024
	ds_read_b128 v[190:193], v240 offset:1536
	v_or_b32_e32 v194, 32, v166
	v_pk_mul_f32 v[172:173], v[118:119], v[196:197] op_sel_hi:[1,0]
	v_pk_mul_f32 v[198:199], v[116:117], v[196:197] op_sel_hi:[1,0]
	v_pk_mul_f32 v[206:207], v[110:111], v[196:197] op_sel_hi:[1,0]
	v_pk_mul_f32 v[208:209], v[108:109], v[196:197] op_sel_hi:[1,0]
	v_pk_mul_f32 v[210:211], v[106:107], v[196:197] op_sel_hi:[1,0]
	v_pk_mul_f32 v[212:213], v[104:105], v[196:197] op_sel_hi:[1,0]
	v_pk_mul_f32 v[214:215], v[98:99], v[196:197] op_sel_hi:[1,0]
	v_pk_mul_f32 v[196:197], v[96:97], v[196:197] op_sel_hi:[1,0]
	v_ashrrev_i32_e32 v195, 31, v194
	v_lshl_add_u64 v[220:221], v[134:135], 0, v[200:201]
	v_lshlrev_b64 v[216:217], 6, v[194:195]
	v_lshl_add_u64 v[220:221], v[220:221], 0, v[154:155]
	v_lshl_add_u64 v[218:219], v[148:149], 0, v[216:217]
	v_lshlrev_b32_e32 v169, s52, v194
	v_and_b32_e32 v169, 0xfff, v169
	v_add_lshl_u32 v200, v169, v167, 8
	v_bitop3_b32 v167, v166, s17, 48 bitop3:0xc8
	v_lshrrev_b32_e32 v167, s44, v167
	s_waitcnt lgkmcnt(3)
	v_pk_mul_f32 v[222:223], v[210:211], v[180:181]
	v_pk_mul_f32 v[224:225], v[212:213], v[178:179]
	s_waitcnt lgkmcnt(2)
	v_pk_mul_f32 v[232:233], v[214:215], v[184:185]
	v_pk_mul_f32 v[234:235], v[196:197], v[182:183]
	v_pk_mul_f32 v[180:181], v[172:173], v[180:181]
	v_pk_mul_f32 v[178:179], v[198:199], v[178:179]
	v_pk_mul_f32 v[184:185], v[206:207], v[184:185]
	v_pk_mul_f32 v[182:183], v[208:209], v[182:183]
	s_waitcnt lgkmcnt(1)
	v_pk_fma_f32 v[172:173], v[172:173], v[188:189], v[222:223] neg_lo:[0,0,1] neg_hi:[0,0,1]
	v_pk_fma_f32 v[198:199], v[198:199], v[186:187], v[224:225] neg_lo:[0,0,1] neg_hi:[0,0,1]
	s_waitcnt lgkmcnt(0)
	v_pk_fma_f32 v[206:207], v[206:207], v[192:193], v[232:233] neg_lo:[0,0,1] neg_hi:[0,0,1]
	v_pk_fma_f32 v[208:209], v[208:209], v[190:191], v[234:235] neg_lo:[0,0,1] neg_hi:[0,0,1]
	v_pk_fma_f32 v[188:189], v[210:211], v[188:189], v[180:181]
	v_pk_fma_f32 v[186:187], v[212:213], v[186:187], v[178:179]
	v_cvt_pk_bf16_f32 v178, v198, v199
	v_cvt_pk_bf16_f32 v179, v172, v173
	v_cvt_pk_bf16_f32 v180, v208, v209
	v_cvt_pk_bf16_f32 v181, v206, v207
	v_pk_fma_f32 v[184:185], v[214:215], v[192:193], v[184:185]
	v_pk_fma_f32 v[182:183], v[196:197], v[190:191], v[182:183]
	v_mov_b32_e32 v96, v178
	v_mov_b32_e32 v97, v179
	v_mov_b32_e32 v98, v180
	v_mov_b32_e32 v99, v181
	v_mov_b32_e32 v108, v220
	v_mov_b32_e32 v109, v221
	v_lshl_add_u64 v[172:173], v[146:147], 0, v[216:217]
	v_pk_mul_f32 v[196:197], v[102:103], v[162:163] op_sel_hi:[1,0]
	v_cvt_pk_bf16_f32 v178, v186, v187
	v_cvt_pk_bf16_f32 v179, v188, v189
	v_cvt_pk_bf16_f32 v180, v182, v183
	v_cvt_pk_bf16_f32 v181, v184, v185
	v_mov_b32_e32 v104, v178
	v_mov_b32_e32 v105, v179
	v_mov_b32_e32 v106, v180
	v_mov_b32_e32 v107, v181
	s_waitcnt vmcnt(20)
	ds_read_b128 v[178:181], v240 offset:2048
	ds_read_b128 v[182:185], v240 offset:2560
	ds_read_b128 v[186:189], v240 offset:3072
	ds_read_b128 v[190:193], v240 offset:3584
	v_or_b32_e32 v172, 48, v166
	v_pk_mul_f32 v[198:199], v[100:101], v[162:163] op_sel_hi:[1,0]
	v_pk_mul_f32 v[210:211], v[90:91], v[162:163] op_sel_hi:[1,0]
	v_pk_mul_f32 v[212:213], v[88:89], v[162:163] op_sel_hi:[1,0]
	v_pk_mul_f32 v[214:215], v[82:83], v[162:163] op_sel_hi:[1,0]
	v_pk_mul_f32 v[216:217], v[80:81], v[162:163] op_sel_hi:[1,0]
	v_pk_mul_f32 v[206:207], v[94:95], v[162:163] op_sel_hi:[1,0]
	v_pk_mul_f32 v[208:209], v[92:93], v[162:163] op_sel_hi:[1,0]
	v_ashrrev_i32_e32 v173, 31, v172
	v_lshl_add_u64 v[220:221], v[134:135], 0, v[200:201]
	v_lshlrev_b64 v[194:195], 6, v[172:173]
	v_lshl_add_u64 v[220:221], v[220:221], 0, v[154:155]
	v_lshl_add_u64 v[218:219], v[148:149], 0, v[194:195]
	v_lshlrev_b32_e32 v169, s52, v172
	v_and_b32_e32 v169, 0xfff, v169
	v_add_lshl_u32 v200, v169, v167, 8
	v_lshl_add_u64 v[134:135], v[134:135], 0, v[200:201]
	v_lshl_add_u64 v[134:135], v[134:135], 0, v[154:155]
	v_ashrrev_i32_e32 v169, 31, v168
	v_lshl_add_u64 v[132:133], v[132:133], 0, v[168:169]
	v_lshrrev_b32_e32 v167, s44, v177
	v_lshlrev_b64 v[132:133], 20, v[132:133]
	v_lshl_add_u64 v[132:133], s[50:51], 0, v[132:133]
	s_waitcnt lgkmcnt(3)
; #define PG8_G __attribute__((address_space(1)))
; __device__ __forceinline__ u32x4 pack8bf(const f32x4 a, const f32x4 b) { u32x4 w; w.x = cvt_pk_bf16(a[0], a[1]); w.y = cvt_pk_bf16(a[2], a[3]); w.z = cvt_pk_bf16(b[0], b[1]); w.w = cvt_pk_bf16(b[2], b[3]); return w; }
;     __device__ __forceinline__ void operator()(const f32x4 (&acc)[2][2][4][2], const Unit& u, int wr, int wc, int fr, int fq, int ui) const {
;     ...
;             const int hh = fq >> 1, i0 = 8 * (fq & 1);
; #pragma unroll
;             for (int ai = 0; ai < 2; ++ai)
; #pragma unroll
;                 for (int m = 0; m < 4; ++m) { const int row = row0 + ai * HALF + m * 16, b = row >> 12, s = row & 4095, sp = ((s & ((1 << sh) - 1)) << (12 - sh)) + (s >> sh);
;                     const f32x4 c0 = *(const PG8_G f32x4*)(cosT + (size_t)row * 16 + i0), c1 = *(const PG8_G f32x4*)(cosT + (size_t)row * 16 + i0 + 4);
;                     const f32x4 s0 = *(const PG8_G f32x4*)(sinT + (size_t)row * 16 + i0), s1 = *(const PG8_G f32x4*)(sinT + (size_t)row * 16 + i0 + 4);
;                     const f32x4 x1a = acc[ai][0][m][0] * r[ai][m], x1b = acc[ai][0][m][1] * r[ai][m], x2a = acc[ai][1][m][0] * r[ai][m], x2b = acc[ai][1][m][1] * r[ai][m];
;                     const f32x4 y1a = x1a * c0 - x2a * s0, y1b = x1b * c1 - x2b * s1, y2a = x2a * c0 + x1a * s0, y2b = x2b * c1 + x1b * s1;
;                     bf16_t* dst = O + ((plane + hh * 4 + b) * 4096 + sp) * 128 + i0;
;                     *(PG8_G u32x4*)dst = pack8bf(y1a, y1b); *(PG8_G u32x4*)(dst + 16) = pack8bf(y2a, y2b); }
	v_pk_mul_f32 v[222:223], v[210:211], v[180:181]
	v_pk_mul_f32 v[224:225], v[212:213], v[178:179]
	s_waitcnt lgkmcnt(2)
	v_pk_mul_f32 v[232:233], v[214:215], v[184:185]
	v_pk_mul_f32 v[234:235], v[216:217], v[182:183]
	v_pk_mul_f32 v[180:181], v[196:197], v[180:181]
	v_pk_mul_f32 v[178:179], v[198:199], v[178:179]
	v_pk_mul_f32 v[184:185], v[206:207], v[184:185]
	v_pk_mul_f32 v[182:183], v[208:209], v[182:183]
	s_waitcnt lgkmcnt(1)
	v_pk_fma_f32 v[196:197], v[196:197], v[188:189], v[222:223] neg_lo:[0,0,1] neg_hi:[0,0,1]
	v_pk_fma_f32 v[198:199], v[198:199], v[186:187], v[224:225] neg_lo:[0,0,1] neg_hi:[0,0,1]
	s_waitcnt lgkmcnt(0)
	v_pk_fma_f32 v[206:207], v[206:207], v[192:193], v[232:233] neg_lo:[0,0,1] neg_hi:[0,0,1]
	v_pk_fma_f32 v[208:209], v[208:209], v[190:191], v[234:235] neg_lo:[0,0,1] neg_hi:[0,0,1]
	v_pk_fma_f32 v[188:189], v[210:211], v[188:189], v[180:181]
	v_pk_fma_f32 v[186:187], v[212:213], v[186:187], v[178:179]
	v_cvt_pk_bf16_f32 v178, v198, v199
	v_cvt_pk_bf16_f32 v179, v196, v197
	v_cvt_pk_bf16_f32 v180, v208, v209
	v_cvt_pk_bf16_f32 v181, v206, v207
	v_pk_fma_f32 v[184:185], v[214:215], v[192:193], v[184:185]
	v_pk_fma_f32 v[182:183], v[216:217], v[190:191], v[182:183]
	v_mov_b32_e32 v80, v178
	v_mov_b32_e32 v81, v179
	v_mov_b32_e32 v82, v180
	v_mov_b32_e32 v83, v181
	v_mov_b32_e32 v92, v220
	v_mov_b32_e32 v93, v221
	v_lshl_add_u64 v[190:191], v[146:147], 0, v[194:195]
	v_mov_b32_e32 v194, v163
	v_cvt_pk_bf16_f32 v178, v186, v187
	v_cvt_pk_bf16_f32 v179, v188, v189
	v_cvt_pk_bf16_f32 v180, v182, v183
	v_cvt_pk_bf16_f32 v181, v184, v185
	v_mov_b32_e32 v88, v178
	v_mov_b32_e32 v89, v179
	v_mov_b32_e32 v90, v180
	v_mov_b32_e32 v91, v181
	s_waitcnt vmcnt(16)
	ds_read_b128 v[178:181], v240 offset:4096
	ds_read_b128 v[182:185], v240 offset:4608
	ds_read_b128 v[186:189], v240 offset:5120
	ds_read_b128 v[190:193], v240 offset:5632
	v_pk_mul_f32 v[172:173], v[86:87], v[194:195] op_sel_hi:[1,0]
	v_pk_mul_f32 v[196:197], v[84:85], v[194:195] op_sel_hi:[1,0]
	v_pk_mul_f32 v[198:199], v[78:79], v[194:195] op_sel_hi:[1,0]
	v_pk_mul_f32 v[206:207], v[76:77], v[194:195] op_sel_hi:[1,0]
	v_pk_mul_f32 v[208:209], v[74:75], v[194:195] op_sel_hi:[1,0]
	v_pk_mul_f32 v[210:211], v[72:73], v[194:195] op_sel_hi:[1,0]
	v_pk_mul_f32 v[212:213], v[70:71], v[194:195] op_sel_hi:[1,0]
	v_pk_mul_f32 v[194:195], v[68:69], v[194:195] op_sel_hi:[1,0]
	v_lshlrev_b64 v[214:215], 6, v[170:171]
	v_lshl_add_u64 v[216:217], v[148:149], 0, v[214:215]
	v_lshlrev_b32_e32 v170, s52, v170
	v_and_b32_e32 v169, 0xfff, v170
	v_add_lshl_u32 v200, v169, v167, 8
	v_lshl_add_u64 v[170:171], v[132:133], 0, v[200:201]
	s_waitcnt lgkmcnt(3)
	v_pk_mul_f32 v[218:219], v[208:209], v[180:181]
	v_pk_mul_f32 v[220:221], v[210:211], v[178:179]
	s_waitcnt lgkmcnt(2)
	v_pk_mul_f32 v[222:223], v[212:213], v[184:185]
	v_pk_mul_f32 v[224:225], v[194:195], v[182:183]
	v_pk_mul_f32 v[180:181], v[172:173], v[180:181]
	v_pk_mul_f32 v[178:179], v[196:197], v[178:179]
	v_pk_mul_f32 v[184:185], v[198:199], v[184:185]
	v_pk_mul_f32 v[182:183], v[206:207], v[182:183]
	s_waitcnt lgkmcnt(1)
	v_pk_fma_f32 v[172:173], v[172:173], v[188:189], v[218:219] neg_lo:[0,0,1] neg_hi:[0,0,1]
	v_pk_fma_f32 v[196:197], v[196:197], v[186:187], v[220:221] neg_lo:[0,0,1] neg_hi:[0,0,1]
	s_waitcnt lgkmcnt(0)
	v_pk_fma_f32 v[198:199], v[198:199], v[192:193], v[222:223] neg_lo:[0,0,1] neg_hi:[0,0,1]
	v_pk_fma_f32 v[206:207], v[206:207], v[190:191], v[224:225] neg_lo:[0,0,1] neg_hi:[0,0,1]
	v_pk_fma_f32 v[188:189], v[208:209], v[188:189], v[180:181]
	v_pk_fma_f32 v[186:187], v[210:211], v[186:187], v[178:179]
	v_cvt_pk_bf16_f32 v178, v196, v197
	v_cvt_pk_bf16_f32 v179, v172, v173
	v_cvt_pk_bf16_f32 v180, v206, v207
	v_cvt_pk_bf16_f32 v181, v198, v199
	v_pk_fma_f32 v[184:185], v[212:213], v[192:193], v[184:185]
	v_pk_fma_f32 v[182:183], v[194:195], v[190:191], v[182:183]
	v_mov_b32_e32 v68, v178
	v_mov_b32_e32 v69, v179
	v_mov_b32_e32 v70, v180
	v_mov_b32_e32 v71, v181
	v_mov_b32_e32 v76, v134
	v_mov_b32_e32 v77, v135
	v_pk_mul_f32 v[206:207], v[58:59], v[160:161] op_sel_hi:[1,0]
	v_pk_mul_f32 v[208:209], v[56:57], v[160:161] op_sel_hi:[1,0]
	v_cvt_pk_bf16_f32 v178, v186, v187
	v_cvt_pk_bf16_f32 v179, v188, v189
	v_cvt_pk_bf16_f32 v180, v182, v183
	v_cvt_pk_bf16_f32 v181, v184, v185
	v_mov_b32_e32 v72, v178
	v_mov_b32_e32 v73, v179
	v_mov_b32_e32 v74, v180
	v_mov_b32_e32 v75, v181
	s_waitcnt vmcnt(12)
	ds_read_b128 v[178:181], v240 offset:6144
	ds_read_b128 v[182:185], v240 offset:6656
	ds_read_b128 v[186:189], v240 offset:7168
	ds_read_b128 v[190:193], v240 offset:7680
	v_lshl_add_u64 v[134:135], v[146:147], 0, v[214:215]
	v_add_u32_e32 v134, 0x90, v166
	v_pk_mul_f32 v[172:173], v[66:67], v[160:161] op_sel_hi:[1,0]
	v_pk_mul_f32 v[194:195], v[64:65], v[160:161] op_sel_hi:[1,0]
	v_pk_mul_f32 v[210:211], v[50:51], v[160:161] op_sel_hi:[1,0]
	v_pk_mul_f32 v[212:213], v[48:49], v[160:161] op_sel_hi:[1,0]
	v_lshl_add_u64 v[218:219], v[170:171], 0, v[154:155]
	v_pk_mul_f32 v[196:197], v[62:63], v[160:161] op_sel_hi:[1,0]
	v_pk_mul_f32 v[198:199], v[60:61], v[160:161] op_sel_hi:[1,0]
	v_ashrrev_i32_e32 v135, 31, v134
	v_lshlrev_b64 v[214:215], 6, v[134:135]
	v_lshl_add_u64 v[216:217], v[148:149], 0, v[214:215]
	v_lshlrev_b32_e32 v167, s52, v134
	v_and_b32_e32 v169, 0xfdf, v134
	v_and_b32_e32 v167, 0xfff, v167
	v_lshrrev_b32_e32 v169, s44, v169
	v_add_lshl_u32 v200, v167, v169, 8
	s_waitcnt lgkmcnt(3)
	v_pk_mul_f32 v[170:171], v[206:207], v[180:181]
	v_pk_mul_f32 v[220:221], v[208:209], v[178:179]
	s_waitcnt lgkmcnt(2)
	v_pk_mul_f32 v[222:223], v[210:211], v[184:185]
	v_pk_mul_f32 v[224:225], v[212:213], v[182:183]
	v_pk_mul_f32 v[180:181], v[172:173], v[180:181]
	s_waitcnt lgkmcnt(1)
; #define PG8_G __attribute__((address_space(1)))
; __device__ __forceinline__ u32x4 pack8bf(const f32x4 a, const f32x4 b) { u32x4 w; w.x = cvt_pk_bf16(a[0], a[1]); w.y = cvt_pk_bf16(a[2], a[3]); w.z = cvt_pk_bf16(b[0], b[1]); w.w = cvt_pk_bf16(b[2], b[3]); return w; }
;     __device__ __forceinline__ void operator()(const f32x4 (&acc)[2][2][4][2], const Unit& u, int wr, int wc, int fr, int fq, int ui) const {
;     ...
;             const int hh = fq >> 1, i0 = 8 * (fq & 1);
; #pragma unroll
;             for (int ai = 0; ai < 2; ++ai)
; #pragma unroll
;                 for (int m = 0; m < 4; ++m) { const int row = row0 + ai * HALF + m * 16, b = row >> 12, s = row & 4095, sp = ((s & ((1 << sh) - 1)) << (12 - sh)) + (s >> sh);
;                     const f32x4 c0 = *(const PG8_G f32x4*)(cosT + (size_t)row * 16 + i0), c1 = *(const PG8_G f32x4*)(cosT + (size_t)row * 16 + i0 + 4);
;                     const f32x4 s0 = *(const PG8_G f32x4*)(sinT + (size_t)row * 16 + i0), s1 = *(const PG8_G f32x4*)(sinT + (size_t)row * 16 + i0 + 4);
;                     const f32x4 x1a = acc[ai][0][m][0] * r[ai][m], x1b = acc[ai][0][m][1] * r[ai][m], x2a = acc[ai][1][m][0] * r[ai][m], x2b = acc[ai][1][m][1] * r[ai][m];
;                     const f32x4 y1a = x1a * c0 - x2a * s0, y1b = x1b * c1 - x2b * s1, y2a = x2a * c0 + x1a * s0, y2b = x2b * c1 + x1b * s1;
;                     bf16_t* dst = O + ((plane + hh * 4 + b) * 4096 + sp) * 128 + i0;
;                     *(PG8_G u32x4*)dst = pack8bf(y1a, y1b); *(PG8_G u32x4*)(dst + 16) = pack8bf(y2a, y2b); }
	v_pk_fma_f32 v[172:173], v[172:173], v[188:189], v[170:171] neg_lo:[0,0,1] neg_hi:[0,0,1]
	v_pk_fma_f32 v[170:171], v[194:195], v[186:187], v[220:221] neg_lo:[0,0,1] neg_hi:[0,0,1]
	v_pk_mul_f32 v[178:179], v[194:195], v[178:179]
	v_pk_mul_f32 v[184:185], v[196:197], v[184:185]
	v_pk_mul_f32 v[182:183], v[198:199], v[182:183]
	s_waitcnt lgkmcnt(0)
	v_pk_fma_f32 v[194:195], v[196:197], v[192:193], v[222:223] neg_lo:[0,0,1] neg_hi:[0,0,1]
	v_pk_fma_f32 v[196:197], v[198:199], v[190:191], v[224:225] neg_lo:[0,0,1] neg_hi:[0,0,1]
	v_cvt_pk_bf16_f32 v170, v170, v171
	v_cvt_pk_bf16_f32 v171, v172, v173
	v_pk_fma_f32 v[180:181], v[206:207], v[188:189], v[180:181]
	v_cvt_pk_bf16_f32 v172, v196, v197
	v_cvt_pk_bf16_f32 v173, v194, v195
	v_pk_fma_f32 v[178:179], v[208:209], v[186:187], v[178:179]
	v_pk_fma_f32 v[184:185], v[210:211], v[192:193], v[184:185]
	v_pk_fma_f32 v[182:183], v[212:213], v[190:191], v[182:183]
	v_mov_b32_e32 v48, v170
	v_mov_b32_e32 v49, v171
	v_mov_b32_e32 v50, v172
	v_mov_b32_e32 v51, v173
	v_mov_b32_e32 v60, v218
	v_mov_b32_e32 v61, v219
	v_lshl_add_u64 v[186:187], v[146:147], 0, v[214:215]
	v_mov_b32_e32 v192, v161
	v_cvt_pk_bf16_f32 v170, v178, v179
	v_cvt_pk_bf16_f32 v171, v180, v181
	v_cvt_pk_bf16_f32 v172, v182, v183
	v_cvt_pk_bf16_f32 v173, v184, v185
	v_mov_b32_e32 v56, v170
	v_mov_b32_e32 v57, v171
	v_mov_b32_e32 v58, v172
	v_mov_b32_e32 v59, v173
	s_waitcnt vmcnt(8)
	ds_read_b128 v[170:173], v240 offset:8192
	ds_read_b128 v[178:181], v240 offset:8704
	ds_read_b128 v[182:185], v240 offset:9216
	ds_read_b128 v[186:189], v240 offset:9728
	v_add_u32_e32 v190, 0xa0, v166
	v_pk_mul_f32 v[134:135], v[54:55], v[192:193] op_sel_hi:[1,0]
	v_pk_mul_f32 v[194:195], v[52:53], v[192:193] op_sel_hi:[1,0]
	v_pk_mul_f32 v[196:197], v[46:47], v[192:193] op_sel_hi:[1,0]
	v_pk_mul_f32 v[198:199], v[44:45], v[192:193] op_sel_hi:[1,0]
	v_pk_mul_f32 v[206:207], v[42:43], v[192:193] op_sel_hi:[1,0]
	v_pk_mul_f32 v[208:209], v[40:41], v[192:193] op_sel_hi:[1,0]
	v_pk_mul_f32 v[210:211], v[34:35], v[192:193] op_sel_hi:[1,0]
	v_pk_mul_f32 v[192:193], v[32:33], v[192:193] op_sel_hi:[1,0]
	v_ashrrev_i32_e32 v191, 31, v190
	v_lshl_add_u64 v[216:217], v[132:133], 0, v[200:201]
	v_lshlrev_b64 v[212:213], 6, v[190:191]
	v_lshl_add_u64 v[216:217], v[216:217], 0, v[154:155]
	v_lshl_add_u64 v[214:215], v[148:149], 0, v[212:213]
	v_lshlrev_b32_e32 v167, s52, v190
	v_and_b32_e32 v169, 0xfef, v190
	v_and_b32_e32 v167, 0xfff, v167
	v_lshrrev_b32_e32 v169, s44, v169
	v_add_lshl_u32 v200, v167, v169, 8
	s_waitcnt lgkmcnt(3)
	v_pk_mul_f32 v[218:219], v[206:207], v[172:173]
	v_pk_mul_f32 v[220:221], v[208:209], v[170:171]
	s_waitcnt lgkmcnt(2)
	v_pk_mul_f32 v[222:223], v[210:211], v[180:181]
	v_pk_mul_f32 v[224:225], v[192:193], v[178:179]
	v_pk_mul_f32 v[172:173], v[134:135], v[172:173]
	v_pk_mul_f32 v[170:171], v[194:195], v[170:171]
	v_pk_mul_f32 v[180:181], v[196:197], v[180:181]
	v_pk_mul_f32 v[178:179], v[198:199], v[178:179]
	s_waitcnt lgkmcnt(1)
	v_pk_fma_f32 v[134:135], v[134:135], v[184:185], v[218:219] neg_lo:[0,0,1] neg_hi:[0,0,1]
	v_pk_fma_f32 v[194:195], v[194:195], v[182:183], v[220:221] neg_lo:[0,0,1] neg_hi:[0,0,1]
	s_waitcnt lgkmcnt(0)
	v_pk_fma_f32 v[196:197], v[196:197], v[188:189], v[222:223] neg_lo:[0,0,1] neg_hi:[0,0,1]
	v_pk_fma_f32 v[198:199], v[198:199], v[186:187], v[224:225] neg_lo:[0,0,1] neg_hi:[0,0,1]
	v_pk_fma_f32 v[184:185], v[206:207], v[184:185], v[172:173]
	v_pk_fma_f32 v[182:183], v[208:209], v[182:183], v[170:171]
	v_cvt_pk_bf16_f32 v170, v194, v195
	v_cvt_pk_bf16_f32 v171, v134, v135
	v_cvt_pk_bf16_f32 v172, v198, v199
	v_cvt_pk_bf16_f32 v173, v196, v197
	v_pk_fma_f32 v[180:181], v[210:211], v[188:189], v[180:181]
	v_pk_fma_f32 v[178:179], v[192:193], v[186:187], v[178:179]
	v_mov_b32_e32 v32, v170
	v_mov_b32_e32 v33, v171
	v_mov_b32_e32 v34, v172
	v_mov_b32_e32 v35, v173
	v_mov_b32_e32 v44, v216
	v_mov_b32_e32 v45, v217
	v_lshl_add_u64 v[134:135], v[146:147], 0, v[212:213]
	v_pk_mul_f32 v[192:193], v[38:39], v[158:159] op_sel_hi:[1,0]
	v_cvt_pk_bf16_f32 v170, v182, v183
	v_cvt_pk_bf16_f32 v171, v184, v185
	v_cvt_pk_bf16_f32 v172, v178, v179
	v_cvt_pk_bf16_f32 v173, v180, v181
	v_mov_b32_e32 v40, v170
	v_mov_b32_e32 v41, v171
	v_mov_b32_e32 v42, v172
	v_mov_b32_e32 v43, v173
	s_waitcnt vmcnt(4)
	ds_read_b128 v[170:173], v240 offset:10240
	ds_read_b128 v[178:181], v240 offset:10752
	ds_read_b128 v[182:185], v240 offset:11264
	ds_read_b128 v[186:189], v240 offset:11776
	v_add_u32_e32 v134, 0xb0, v166
	v_pk_mul_f32 v[194:195], v[36:37], v[158:159] op_sel_hi:[1,0]
	v_pk_mul_f32 v[206:207], v[26:27], v[158:159] op_sel_hi:[1,0]
	v_pk_mul_f32 v[208:209], v[24:25], v[158:159] op_sel_hi:[1,0]
	v_pk_mul_f32 v[210:211], v[18:19], v[158:159] op_sel_hi:[1,0]
	v_pk_mul_f32 v[212:213], v[16:17], v[158:159] op_sel_hi:[1,0]
	v_pk_mul_f32 v[196:197], v[30:31], v[158:159] op_sel_hi:[1,0]
	v_pk_mul_f32 v[198:199], v[28:29], v[158:159] op_sel_hi:[1,0]
	v_ashrrev_i32_e32 v135, 31, v134
	v_lshl_add_u64 v[216:217], v[132:133], 0, v[200:201]
	v_lshlrev_b64 v[190:191], 6, v[134:135]
	v_lshl_add_u64 v[216:217], v[216:217], 0, v[154:155]
	v_lshl_add_u64 v[214:215], v[148:149], 0, v[190:191]
	v_lshlrev_b32_e32 v167, s52, v134
	v_and_b32_e32 v169, 0xfff, v134
	v_and_b32_e32 v167, 0xfff, v167
	v_lshrrev_b32_e32 v169, s44, v169
	v_add_lshl_u32 v200, v167, v169, 8
	v_lshl_add_u64 v[132:133], v[132:133], 0, v[200:201]
	s_waitcnt lgkmcnt(3)
	v_pk_mul_f32 v[218:219], v[206:207], v[172:173]
	v_pk_mul_f32 v[220:221], v[208:209], v[170:171]
	s_waitcnt lgkmcnt(2)
; #define PG8_G __attribute__((address_space(1)))
; __device__ __forceinline__ u32x4 pack8bf(const f32x4 a, const f32x4 b) { u32x4 w; w.x = cvt_pk_bf16(a[0], a[1]); w.y = cvt_pk_bf16(a[2], a[3]); w.z = cvt_pk_bf16(b[0], b[1]); w.w = cvt_pk_bf16(b[2], b[3]); return w; }
;     __device__ __forceinline__ void operator()(const f32x4 (&acc)[2][2][4][2], const Unit& u, int wr, int wc, int fr, int fq, int ui) const {
;     ...
;             const int hh = fq >> 1, i0 = 8 * (fq & 1);
; #pragma unroll
;             for (int ai = 0; ai < 2; ++ai)
; #pragma unroll
;                 for (int m = 0; m < 4; ++m) { const int row = row0 + ai * HALF + m * 16, b = row >> 12, s = row & 4095, sp = ((s & ((1 << sh) - 1)) << (12 - sh)) + (s >> sh);
;                     const f32x4 c0 = *(const PG8_G f32x4*)(cosT + (size_t)row * 16 + i0), c1 = *(const PG8_G f32x4*)(cosT + (size_t)row * 16 + i0 + 4);
;                     const f32x4 s0 = *(const PG8_G f32x4*)(sinT + (size_t)row * 16 + i0), s1 = *(const PG8_G f32x4*)(sinT + (size_t)row * 16 + i0 + 4);
;                     const f32x4 x1a = acc[ai][0][m][0] * r[ai][m], x1b = acc[ai][0][m][1] * r[ai][m], x2a = acc[ai][1][m][0] * r[ai][m], x2b = acc[ai][1][m][1] * r[ai][m];
;                     const f32x4 y1a = x1a * c0 - x2a * s0, y1b = x1b * c1 - x2b * s1, y2a = x2a * c0 + x1a * s0, y2b = x2b * c1 + x1b * s1;
;                     bf16_t* dst = O + ((plane + hh * 4 + b) * 4096 + sp) * 128 + i0;
;                     *(PG8_G u32x4*)dst = pack8bf(y1a, y1b); *(PG8_G u32x4*)(dst + 16) = pack8bf(y2a, y2b); }
	v_pk_mul_f32 v[222:223], v[210:211], v[180:181]
	v_pk_mul_f32 v[224:225], v[212:213], v[178:179]
	v_pk_mul_f32 v[172:173], v[192:193], v[172:173]
	v_pk_mul_f32 v[170:171], v[194:195], v[170:171]
	v_pk_mul_f32 v[180:181], v[196:197], v[180:181]
	v_pk_mul_f32 v[178:179], v[198:199], v[178:179]
	s_waitcnt lgkmcnt(1)
	v_pk_fma_f32 v[192:193], v[192:193], v[184:185], v[218:219] neg_lo:[0,0,1] neg_hi:[0,0,1]
	v_pk_fma_f32 v[194:195], v[194:195], v[182:183], v[220:221] neg_lo:[0,0,1] neg_hi:[0,0,1]
	s_waitcnt lgkmcnt(0)
	v_pk_fma_f32 v[196:197], v[196:197], v[188:189], v[222:223] neg_lo:[0,0,1] neg_hi:[0,0,1]
	v_pk_fma_f32 v[198:199], v[198:199], v[186:187], v[224:225] neg_lo:[0,0,1] neg_hi:[0,0,1]
	v_pk_fma_f32 v[184:185], v[206:207], v[184:185], v[172:173]
	v_pk_fma_f32 v[182:183], v[208:209], v[182:183], v[170:171]
	v_cvt_pk_bf16_f32 v170, v194, v195
	v_cvt_pk_bf16_f32 v171, v192, v193
	v_cvt_pk_bf16_f32 v172, v198, v199
	v_cvt_pk_bf16_f32 v173, v196, v197
	v_pk_fma_f32 v[180:181], v[210:211], v[188:189], v[180:181]
	v_pk_fma_f32 v[178:179], v[212:213], v[186:187], v[178:179]
	v_mov_b32_e32 v16, v170
	v_mov_b32_e32 v17, v171
	v_mov_b32_e32 v18, v172
	v_mov_b32_e32 v19, v173
	v_mov_b32_e32 v28, v216
	v_mov_b32_e32 v29, v217
	v_lshl_add_u64 v[212:213], v[132:133], 0, v[154:155]
	s_nop 0
	v_cvt_pk_bf16_f32 v170, v182, v183
	v_cvt_pk_bf16_f32 v171, v184, v185
	v_cvt_pk_bf16_f32 v172, v178, v179
	v_cvt_pk_bf16_f32 v173, v180, v181
	v_mov_b32_e32 v24, v170
	v_mov_b32_e32 v25, v171
	v_mov_b32_e32 v26, v172
	v_mov_b32_e32 v27, v173
	s_waitcnt vmcnt(0)
	ds_read_b128 v[178:181], v240 offset:12288
	ds_read_b128 v[182:185], v240 offset:12800
	ds_read_b128 v[186:189], v240 offset:13312
	ds_read_b128 v[190:193], v240 offset:13824
	v_lshl_add_u64 v[170:171], v[146:147], 0, v[190:191]
	v_mov_b32_e32 v170, v159
	v_pk_mul_f32 v[206:207], v[10:11], v[170:171] op_sel_hi:[1,0]
	v_pk_mul_f32 v[208:209], v[8:9], v[170:171] op_sel_hi:[1,0]
	v_pk_mul_f32 v[134:135], v[22:23], v[170:171] op_sel_hi:[1,0]
	v_pk_mul_f32 v[194:195], v[20:21], v[170:171] op_sel_hi:[1,0]
	v_pk_mul_f32 v[196:197], v[14:15], v[170:171] op_sel_hi:[1,0]
	v_pk_mul_f32 v[198:199], v[12:13], v[170:171] op_sel_hi:[1,0]
	v_pk_mul_f32 v[210:211], v[6:7], v[170:171] op_sel_hi:[1,0]
	v_pk_mul_f32 v[170:171], v[4:5], v[170:171] op_sel_hi:[1,0]
	v_lshl_add_u64 v[172:173], v[212:213], 0, 32
	s_waitcnt lgkmcnt(3)
	v_pk_mul_f32 v[132:133], v[206:207], v[180:181]
	v_pk_mul_f32 v[214:215], v[208:209], v[178:179]
	s_waitcnt lgkmcnt(2)
	v_pk_mul_f32 v[216:217], v[210:211], v[184:185]
	v_pk_mul_f32 v[218:219], v[170:171], v[182:183]
	v_pk_mul_f32 v[180:181], v[134:135], v[180:181]
	s_waitcnt lgkmcnt(1)
	v_pk_fma_f32 v[134:135], v[134:135], v[188:189], v[132:133] neg_lo:[0,0,1] neg_hi:[0,0,1]
	v_pk_fma_f32 v[132:133], v[194:195], v[186:187], v[214:215] neg_lo:[0,0,1] neg_hi:[0,0,1]
	v_pk_mul_f32 v[178:179], v[194:195], v[178:179]
	v_pk_mul_f32 v[184:185], v[196:197], v[184:185]
	v_pk_mul_f32 v[182:183], v[198:199], v[182:183]
	s_waitcnt lgkmcnt(0)
	v_pk_fma_f32 v[194:195], v[196:197], v[192:193], v[216:217] neg_lo:[0,0,1] neg_hi:[0,0,1]
	v_pk_fma_f32 v[196:197], v[198:199], v[190:191], v[218:219] neg_lo:[0,0,1] neg_hi:[0,0,1]
	v_cvt_pk_bf16_f32 v132, v132, v133
	v_cvt_pk_bf16_f32 v133, v134, v135
	v_pk_fma_f32 v[180:181], v[206:207], v[188:189], v[180:181]
	v_cvt_pk_bf16_f32 v134, v196, v197
	v_cvt_pk_bf16_f32 v135, v194, v195
	v_pk_fma_f32 v[178:179], v[208:209], v[186:187], v[178:179]
	v_pk_fma_f32 v[184:185], v[210:211], v[192:193], v[184:185]
	v_pk_fma_f32 v[170:171], v[170:171], v[190:191], v[182:183]
	global_store_dwordx4 v[212:213], v[132:135], off
	s_nop 1
	v_cvt_pk_bf16_f32 v132, v178, v179
	v_cvt_pk_bf16_f32 v133, v180, v181
	v_cvt_pk_bf16_f32 v134, v170, v171
	v_cvt_pk_bf16_f32 v135, v184, v185
	global_store_dwordx4 v[124:125], v[112:115], off
	global_store_dwordx4 v[124:125], v[120:123], off offset:32
	global_store_dwordx4 v[108:109], v[96:99], off
	global_store_dwordx4 v[108:109], v[104:107], off offset:32
	global_store_dwordx4 v[92:93], v[80:83], off
	global_store_dwordx4 v[92:93], v[88:91], off offset:32
	global_store_dwordx4 v[76:77], v[68:71], off
	global_store_dwordx4 v[76:77], v[72:75], off offset:32
	global_store_dwordx4 v[60:61], v[48:51], off
	global_store_dwordx4 v[60:61], v[56:59], off offset:32
	global_store_dwordx4 v[44:45], v[32:35], off
	global_store_dwordx4 v[44:45], v[40:43], off offset:32
	global_store_dwordx4 v[28:29], v[16:19], off
	global_store_dwordx4 v[28:29], v[24:27], off offset:32
	s_cbranch_execnz .LBB0_758
; #define PG8_G __attribute__((address_space(1)))
; __device__ __forceinline__ u32x4 pack8bf(const f32x4 a, const f32x4 b) { u32x4 w; w.x = cvt_pk_bf16(a[0], a[1]); w.y = cvt_pk_bf16(a[2], a[3]); w.z = cvt_pk_bf16(b[0], b[1]); w.w = cvt_pk_bf16(b[2], b[3]); return w; }
;     __device__ __forceinline__ void operator()(const f32x4 (&acc)[2][2][4][2], const Unit& u, int wr, int wc, int fr, int fq, int ui) const {
;     ...
;         if (t == 2 || wc != 0) {
;             const int dim0 = wc * 32 + 8 * fq;
; #pragma unroll
;             for (int ai = 0; ai < 2; ++ai)
; #pragma unroll
;                 for (int m = 0; m < 4; ++m) { const int row = row0 + ai * HALF + m * 16, b = row >> 12, s = row & 4095, sp = ((s & ((1 << sh) - 1)) << (12 - sh)) + (s >> sh);
; #pragma unroll
;                     for (int bj = 0; bj < 2; ++bj) *(PG8_G u32x4*)(O + ((plane + bj * 4 + b) * 4096 + sp) * 128 + dim0) = pack8bf(acc[ai][bj][m][0] * r[ai][m], acc[ai][bj][m][1] * r[ai][m]); }
.LBB0_760:
	s_barrier
	v_or_b32_e32 v132, 48, v177
	s_sub_i32 s48, 12, s44
	v_lshlrev_b32_e32 v133, s48, v132
	v_lshrrev_b32_e32 v167, s44, v132
	v_or_b32_e32 v132, 32, v177
	v_and_b32_e32 v155, 0xfff, v133
	v_lshlrev_b32_e32 v133, s48, v132
	v_lshrrev_b32_e32 v171, s44, v132
	v_or_b32_e32 v132, 16, v177
	v_and_b32_e32 v170, 0xfff, v133
	v_lshlrev_b32_e32 v133, s48, v132
	v_ashrrev_i32_e32 v169, 31, v168
	v_lshlrev_b32_e32 v134, s48, v177
	v_and_b32_e32 v172, 0xfff, v133
	v_lshrrev_b32_e32 v173, s44, v132
	v_lshl_add_u64 v[132:133], s[68:69], 0, v[168:169]
	v_and_b32_e32 v168, 0xfff, v134
	v_or_b32_e32 v134, 48, v176
	v_lshlrev_b32_e32 v135, s48, v134
	v_lshrrev_b32_e32 v178, s44, v134
	v_or_b32_e32 v134, 32, v176
	v_lshrrev_b32_e32 v169, s44, v177
	v_and_b32_e32 v177, 0xfff, v135
	v_lshlrev_b32_e32 v135, s48, v134
	v_lshrrev_b32_e32 v180, s44, v134
	v_or_b32_e32 v134, 16, v176
	s_ashr_i32 s25, s25, 12
	v_lshrrev_b32_e32 v181, s44, v134
	s_ashr_i32 s44, s25, 31
	s_add_u32 s52, s68, s25
	s_addc_u32 s53, s69, s44
	v_and_b32_e32 v179, 0xfff, v135
	v_lshlrev_b32_e32 v135, s48, v134
	s_lshl_b64 s[52:53], s[52:53], 20
	v_lshlrev_b32_e32 v134, s48, v166
	v_and_b32_e32 v166, 0xfff, v134
	s_add_u32 s68, s50, s52
	s_waitcnt lgkmcnt(0)
	v_pk_mul_f32 v[128:129], v[128:129], v[164:165] op_sel_hi:[1,0]
	s_addc_u32 s69, s51, s53
	v_add_lshl_u32 v200, v166, v157, 8
	v_and_b32_e32 v176, 0xfff, v135
	v_pk_mul_f32 v[134:135], v[126:127], v[164:165] op_sel_hi:[1,0]
	v_pk_mul_f32 v[126:127], v[124:125], v[164:165] op_sel_hi:[1,0]
	v_cvt_pk_bf16_f32 v124, v128, v129
	v_lshl_add_u64 v[128:129], s[68:69], 0, v[200:201]
	v_mov_b32_e32 v157, v201
	s_add_u32 s76, s68, 0x400000
	v_pk_mul_f32 v[130:131], v[130:131], v[164:165] op_sel_hi:[1,0]
	v_lshl_add_u64 v[128:129], v[128:129], 0, v[156:157]
	v_cvt_pk_bf16_f32 v125, v130, v131
	v_pk_mul_f32 v[120:121], v[120:121], v[164:165] op_sel_hi:[1,0]
	s_addc_u32 s77, s69, 0
	v_cvt_pk_bf16_f32 v126, v126, v127
	v_cvt_pk_bf16_f32 v127, v134, v135
	global_store_dwordx4 v[128:129], v[124:127], off
	v_pk_mul_f32 v[122:123], v[122:123], v[164:165] op_sel_hi:[1,0]
	v_pk_mul_f32 v[88:89], v[88:89], v[162:163] op_sel_hi:[1,0]
	v_pk_mul_f32 v[124:125], v[114:115], v[164:165] op_sel_hi:[1,0]
	v_pk_mul_f32 v[114:115], v[112:113], v[164:165] op_sel_hi:[1,0]
	v_cvt_pk_bf16_f32 v112, v120, v121
	v_lshl_add_u64 v[120:121], s[76:77], 0, v[200:201]
	v_lshl_add_u64 v[120:121], v[120:121], 0, v[156:157]
	v_cvt_pk_bf16_f32 v113, v122, v123
	v_cvt_pk_bf16_f32 v114, v114, v115
	v_cvt_pk_bf16_f32 v115, v124, v125
	global_store_dwordx4 v[120:121], v[112:115], off
	v_add_lshl_u32 v200, v176, v181, 8
	v_pk_mul_f32 v[90:91], v[90:91], v[162:163] op_sel_hi:[1,0]
	v_mov_b32_e32 v112, v165
	v_pk_mul_f32 v[114:115], v[118:119], v[112:113] op_sel_hi:[1,0]
	v_pk_mul_f32 v[116:117], v[116:117], v[112:113] op_sel_hi:[1,0]
	v_pk_mul_f32 v[118:119], v[110:111], v[112:113] op_sel_hi:[1,0]
	v_pk_mul_f32 v[110:111], v[108:109], v[112:113] op_sel_hi:[1,0]
	v_cvt_pk_bf16_f32 v108, v116, v117
	v_cvt_pk_bf16_f32 v109, v114, v115
	v_lshl_add_u64 v[114:115], s[68:69], 0, v[200:201]
	v_lshl_add_u64 v[114:115], v[114:115], 0, v[156:157]
	v_pk_mul_f32 v[104:105], v[104:105], v[112:113] op_sel_hi:[1,0]
	v_cvt_pk_bf16_f32 v110, v110, v111
	v_cvt_pk_bf16_f32 v111, v118, v119
	global_store_dwordx4 v[114:115], v[108:111], off
	v_pk_mul_f32 v[106:107], v[106:107], v[112:113] op_sel_hi:[1,0]
	v_lshlrev_b64 v[132:133], 20, v[132:133]
	v_pk_mul_f32 v[108:109], v[98:99], v[112:113] op_sel_hi:[1,0]
	v_pk_mul_f32 v[98:99], v[96:97], v[112:113] op_sel_hi:[1,0]
	v_cvt_pk_bf16_f32 v96, v104, v105
	v_lshl_add_u64 v[104:105], s[76:77], 0, v[200:201]
	v_cvt_pk_bf16_f32 v97, v106, v107
	v_lshl_add_u64 v[104:105], v[104:105], 0, v[156:157]
	v_cvt_pk_bf16_f32 v98, v98, v99
	v_cvt_pk_bf16_f32 v99, v108, v109
	global_store_dwordx4 v[104:105], v[96:99], off
	v_add_lshl_u32 v200, v179, v180, 8
	v_pk_mul_f32 v[64:65], v[64:65], v[160:161] op_sel_hi:[1,0]
	v_pk_mul_f32 v[96:97], v[102:103], v[162:163] op_sel_hi:[1,0]
	v_pk_mul_f32 v[98:99], v[100:101], v[162:163] op_sel_hi:[1,0]
	v_pk_mul_f32 v[100:101], v[94:95], v[162:163] op_sel_hi:[1,0]
	v_pk_mul_f32 v[94:95], v[92:93], v[162:163] op_sel_hi:[1,0]
	v_cvt_pk_bf16_f32 v92, v98, v99
	v_cvt_pk_bf16_f32 v93, v96, v97
	v_lshl_add_u64 v[96:97], s[68:69], 0, v[200:201]
	v_lshl_add_u64 v[96:97], v[96:97], 0, v[156:157]
	v_cvt_pk_bf16_f32 v94, v94, v95
	v_cvt_pk_bf16_f32 v95, v100, v101
	global_store_dwordx4 v[96:97], v[92:95], off
	v_pk_mul_f32 v[66:67], v[66:67], v[160:161] op_sel_hi:[1,0]
	v_pk_mul_f32 v[56:57], v[56:57], v[160:161] op_sel_hi:[1,0]
	v_pk_mul_f32 v[92:93], v[82:83], v[162:163] op_sel_hi:[1,0]
	v_pk_mul_f32 v[82:83], v[80:81], v[162:163] op_sel_hi:[1,0]
	v_cvt_pk_bf16_f32 v80, v88, v89
	v_lshl_add_u64 v[88:89], s[76:77], 0, v[200:201]
	v_lshl_add_u64 v[88:89], v[88:89], 0, v[156:157]
	v_cvt_pk_bf16_f32 v81, v90, v91
	v_cvt_pk_bf16_f32 v82, v82, v83
	v_cvt_pk_bf16_f32 v83, v92, v93
	global_store_dwordx4 v[88:89], v[80:83], off
	v_add_lshl_u32 v200, v177, v178, 8
	s_mov_b64 s[52:53], 0x400000
	v_mov_b32_e32 v80, v163
	v_pk_mul_f32 v[82:83], v[86:87], v[80:81] op_sel_hi:[1,0]
	v_pk_mul_f32 v[84:85], v[84:85], v[80:81] op_sel_hi:[1,0]
; #define PG8_G __attribute__((address_space(1)))
; __device__ __forceinline__ u32x4 pack8bf(const f32x4 a, const f32x4 b) { u32x4 w; w.x = cvt_pk_bf16(a[0], a[1]); w.y = cvt_pk_bf16(a[2], a[3]); w.z = cvt_pk_bf16(b[0], b[1]); w.w = cvt_pk_bf16(b[2], b[3]); return w; }
;     __device__ __forceinline__ void operator()(const f32x4 (&acc)[2][2][4][2], const Unit& u, int wr, int wc, int fr, int fq, int ui) const {
;     ...
;         if (t == 2 || wc != 0) {
;             const int dim0 = wc * 32 + 8 * fq;
; #pragma unroll
;             for (int ai = 0; ai < 2; ++ai)
; #pragma unroll
;                 for (int m = 0; m < 4; ++m) { const int row = row0 + ai * HALF + m * 16, b = row >> 12, s = row & 4095, sp = ((s & ((1 << sh) - 1)) << (12 - sh)) + (s >> sh);
; #pragma unroll
;                     for (int bj = 0; bj < 2; ++bj) *(PG8_G u32x4*)(O + ((plane + bj * 4 + b) * 4096 + sp) * 128 + dim0) = pack8bf(acc[ai][bj][m][0] * r[ai][m], acc[ai][bj][m][1] * r[ai][m]); }
	v_pk_mul_f32 v[86:87], v[78:79], v[80:81] op_sel_hi:[1,0]
	v_pk_mul_f32 v[78:79], v[76:77], v[80:81] op_sel_hi:[1,0]
	v_cvt_pk_bf16_f32 v76, v84, v85
	v_cvt_pk_bf16_f32 v77, v82, v83
	v_lshl_add_u64 v[82:83], s[68:69], 0, v[200:201]
	v_lshl_add_u64 v[82:83], v[82:83], 0, v[156:157]
	v_pk_mul_f32 v[72:73], v[72:73], v[80:81] op_sel_hi:[1,0]
	v_cvt_pk_bf16_f32 v78, v78, v79
	v_cvt_pk_bf16_f32 v79, v86, v87
	global_store_dwordx4 v[82:83], v[76:79], off
	v_pk_mul_f32 v[74:75], v[74:75], v[80:81] op_sel_hi:[1,0]
	v_pk_mul_f32 v[58:59], v[58:59], v[160:161] op_sel_hi:[1,0]
	v_pk_mul_f32 v[76:77], v[70:71], v[80:81] op_sel_hi:[1,0]
	v_pk_mul_f32 v[70:71], v[68:69], v[80:81] op_sel_hi:[1,0]
	v_cvt_pk_bf16_f32 v68, v72, v73
	v_lshl_add_u64 v[72:73], s[76:77], 0, v[200:201]
	v_cvt_pk_bf16_f32 v69, v74, v75
	v_lshl_add_u64 v[72:73], v[72:73], 0, v[156:157]
	v_cvt_pk_bf16_f32 v70, v70, v71
	v_cvt_pk_bf16_f32 v71, v76, v77
	global_store_dwordx4 v[72:73], v[68:71], off
	v_add_lshl_u32 v200, v168, v169, 8
	v_pk_mul_f32 v[24:25], v[24:25], v[158:159] op_sel_hi:[1,0]
	v_pk_mul_f32 v[68:69], v[62:63], v[160:161] op_sel_hi:[1,0]
	v_pk_mul_f32 v[62:63], v[60:61], v[160:161] op_sel_hi:[1,0]
	v_cvt_pk_bf16_f32 v60, v64, v65
	v_lshl_add_u64 v[64:65], s[50:51], 0, v[132:133]
	v_cvt_pk_bf16_f32 v61, v66, v67
	v_lshl_add_u64 v[66:67], v[64:65], 0, v[200:201]
	v_lshl_add_u64 v[66:67], v[66:67], 0, v[156:157]
	v_cvt_pk_bf16_f32 v62, v62, v63
	v_cvt_pk_bf16_f32 v63, v68, v69
	global_store_dwordx4 v[66:67], v[60:63], off
	v_pk_mul_f32 v[26:27], v[26:27], v[158:159] op_sel_hi:[1,0]
	s_nop 0
	v_pk_mul_f32 v[60:61], v[50:51], v[160:161] op_sel_hi:[1,0]
	v_pk_mul_f32 v[50:51], v[48:49], v[160:161] op_sel_hi:[1,0]
	v_cvt_pk_bf16_f32 v48, v56, v57
	v_lshl_add_u64 v[56:57], v[64:65], 0, s[52:53]
	v_cvt_pk_bf16_f32 v49, v58, v59
	v_lshl_add_u64 v[58:59], v[56:57], 0, v[200:201]
	v_lshl_add_u64 v[58:59], v[58:59], 0, v[156:157]
	v_cvt_pk_bf16_f32 v50, v50, v51
	v_cvt_pk_bf16_f32 v51, v60, v61
	global_store_dwordx4 v[58:59], v[48:51], off
	v_add_lshl_u32 v200, v172, v173, 8
	s_nop 0
	v_mov_b32_e32 v48, v161
	v_pk_mul_f32 v[50:51], v[54:55], v[48:49] op_sel_hi:[1,0]
	v_pk_mul_f32 v[52:53], v[52:53], v[48:49] op_sel_hi:[1,0]
	v_pk_mul_f32 v[54:55], v[46:47], v[48:49] op_sel_hi:[1,0]
	v_pk_mul_f32 v[46:47], v[44:45], v[48:49] op_sel_hi:[1,0]
	v_cvt_pk_bf16_f32 v44, v52, v53
	v_cvt_pk_bf16_f32 v45, v50, v51
	v_lshl_add_u64 v[50:51], v[64:65], 0, v[200:201]
	v_lshl_add_u64 v[50:51], v[50:51], 0, v[156:157]
	v_pk_mul_f32 v[40:41], v[40:41], v[48:49] op_sel_hi:[1,0]
	v_cvt_pk_bf16_f32 v46, v46, v47
	v_cvt_pk_bf16_f32 v47, v54, v55
	global_store_dwordx4 v[50:51], v[44:47], off
	v_pk_mul_f32 v[42:43], v[42:43], v[48:49] op_sel_hi:[1,0]
	s_nop 0
	v_pk_mul_f32 v[44:45], v[34:35], v[48:49] op_sel_hi:[1,0]
	v_pk_mul_f32 v[34:35], v[32:33], v[48:49] op_sel_hi:[1,0]
	v_cvt_pk_bf16_f32 v32, v40, v41
	v_lshl_add_u64 v[40:41], v[56:57], 0, v[200:201]
	v_cvt_pk_bf16_f32 v33, v42, v43
	v_lshl_add_u64 v[40:41], v[40:41], 0, v[156:157]
	v_cvt_pk_bf16_f32 v34, v34, v35
	v_cvt_pk_bf16_f32 v35, v44, v45
	global_store_dwordx4 v[40:41], v[32:35], off
	v_add_lshl_u32 v200, v170, v171, 8
	s_nop 0
	v_pk_mul_f32 v[32:33], v[38:39], v[158:159] op_sel_hi:[1,0]
	v_pk_mul_f32 v[34:35], v[36:37], v[158:159] op_sel_hi:[1,0]
	v_pk_mul_f32 v[36:37], v[30:31], v[158:159] op_sel_hi:[1,0]
	v_pk_mul_f32 v[30:31], v[28:29], v[158:159] op_sel_hi:[1,0]
	v_cvt_pk_bf16_f32 v28, v34, v35
	v_cvt_pk_bf16_f32 v29, v32, v33
	v_lshl_add_u64 v[32:33], v[64:65], 0, v[200:201]
	v_lshl_add_u64 v[32:33], v[32:33], 0, v[156:157]
	v_cvt_pk_bf16_f32 v30, v30, v31
	v_cvt_pk_bf16_f32 v31, v36, v37
	global_store_dwordx4 v[32:33], v[28:31], off
	s_nop 1
	v_pk_mul_f32 v[28:29], v[18:19], v[158:159] op_sel_hi:[1,0]
	v_pk_mul_f32 v[18:19], v[16:17], v[158:159] op_sel_hi:[1,0]
	v_cvt_pk_bf16_f32 v16, v24, v25
	v_lshl_add_u64 v[24:25], v[56:57], 0, v[200:201]
	v_lshl_add_u64 v[24:25], v[24:25], 0, v[156:157]
	v_cvt_pk_bf16_f32 v17, v26, v27
	v_cvt_pk_bf16_f32 v18, v18, v19
	v_cvt_pk_bf16_f32 v19, v28, v29
	global_store_dwordx4 v[24:25], v[16:19], off
	v_add_lshl_u32 v200, v155, v167, 8
	s_nop 0
	v_mov_b32_e32 v16, v159
	v_pk_mul_f32 v[18:19], v[22:23], v[16:17] op_sel_hi:[1,0]
	v_pk_mul_f32 v[20:21], v[20:21], v[16:17] op_sel_hi:[1,0]
	v_pk_mul_f32 v[22:23], v[14:15], v[16:17] op_sel_hi:[1,0]
	v_pk_mul_f32 v[14:15], v[12:13], v[16:17] op_sel_hi:[1,0]
	v_cvt_pk_bf16_f32 v12, v20, v21
	v_cvt_pk_bf16_f32 v13, v18, v19
	v_lshl_add_u64 v[18:19], v[64:65], 0, v[200:201]
	v_lshl_add_u64 v[18:19], v[18:19], 0, v[156:157]
	v_pk_mul_f32 v[4:5], v[4:5], v[16:17] op_sel_hi:[1,0]
	v_cvt_pk_bf16_f32 v14, v14, v15
	v_cvt_pk_bf16_f32 v15, v22, v23
	global_store_dwordx4 v[18:19], v[12:15], off
	v_pk_mul_f32 v[10:11], v[10:11], v[16:17] op_sel_hi:[1,0]
	v_pk_mul_f32 v[8:9], v[8:9], v[16:17] op_sel_hi:[1,0]
	v_pk_mul_f32 v[6:7], v[6:7], v[16:17] op_sel_hi:[1,0]
	v_cvt_pk_bf16_f32 v132, v8, v9
	v_cvt_pk_bf16_f32 v133, v10, v11
	v_cvt_pk_bf16_f32 v134, v4, v5
	v_lshl_add_u64 v[4:5], v[56:57], 0, v[200:201]
	v_lshl_add_u64 v[172:173], v[4:5], 0, v[156:157]
	v_cvt_pk_bf16_f32 v135, v6, v7
	s_andn2_b64 vcc, exec, s[8:9]
	s_mov_b64 s[8:9], -1
	global_store_dwordx4 v[172:173], v[132:135], off
	s_cbranch_vccnz .LBB0_749
